# G1 K-loop: direct global->LDS loads (global_load_lds_dwordx4) instead of VGPR staging + ds_write_b128; bank swizzle moved to the source address
# speedup vs baseline: 1.0144x; 1.0144x over previous
; __device__ __forceinline__ int otid() { int t = threadIdx.x; asm volatile("" : "+v"(t)); return t; }
; __device__ __forceinline__ bool tile_at(int it, int MT, int NTn, int& mt, int& nt) {
;   const int G = gridDim.x;
;   const int nx = (G % 8 == 0) ? 8 : 1;
;   const int x = blockIdx.x % nx, j = blockIdx.x / nx, nloc = G / nx;
;   const int ch = x + nx * it;
;   const int q = ch * nloc + j;
;   if (q >= MT * NTn) return false;
;   const int gs = 8 * NTn;
;   const int g = q / gs, rem = q - g * gs;
;   const int gsz = min(8, MT - g * 8);
;   nt = rem / gsz;
;   mt = g * 8 + (rem - nt * gsz);
;   return true;
; }
; __device__ __forceinline__ void gemm_core_big(const bf16_t* __restrict__ A, int lda, const bf16_t* __restrict__ Bt, int ldb,
;                                               int K, f32x4 (&acc)[8][4], char* smem) {
;     ...
;   const int tid = otid(), lane = tid & 63, wave = tid >> 6;
;   const int wm = wave >> 1, wn = wave & 1;
;   const int lr = tid >> 3, lc = (tid & 7) * 8;
;   const bf16_t* ap = A + (size_t)lr * lda + lc;
;   const bf16_t* bp = Bt + (size_t)lr * ldb + lc;
;   const int nk = K >> 6;
;   const int fr = lane & 15, fq = (lane >> 4) * 8;
;   const int rswz = (fr >> 1) & 7, wswz = (lr >> 1) & 7;
;   const int fo0 = (((lane >> 4)) ^ rswz) * 8, fo1 = ((4 + (lane >> 4)) ^ rswz) * 8;
;   const bf16_t* cA = sA + (wm * 128 + fr) * LDS_STRIDE;
;   const bf16_t* cB = sB + (wn * 64 + fr) * LDS_STRIDE;
;   bf16_t* wA = sA + lr * LDS_STRIDE + (((tid & 7) ^ wswz) * 8);
;   bf16_t* wB = sB + lr * LDS_STRIDE + (((tid & 7) ^ wswz) * 8);
;   u32x4 ra[8], rb[4];
.LBB0_709:
	s_lshl_b32 s12, s23, s24
	s_add_i32 s12, s12, s22
	s_mul_i32 s14, s12, s16
	s_add_i32 s14, s14, s25
	s_cmpk_gt_i32 s14, 0x11c5
	s_mov_b64 s[12:13], -1
	s_cbranch_scc1 .LBB0_708
	s_mul_hi_i32 s12, s14, 0xea0ea0eb
	s_add_i32 s12, s12, s14
	s_lshr_b32 s13, s12, 31
	s_ashr_i32 s12, s12, 9
	s_add_i32 s12, s12, s13
	s_lshl_b32 s13, s12, 3
	s_sub_i32 s15, 0x41, s13
	s_min_u32 s15, s15, 8
	v_cvt_f32_ubyte0_e32 v0, s15
	v_rcp_iflag_f32_e32 v0, v0
	s_sub_i32 s26, 0, s15
	s_mulk_i32 s12, 0xfdd0
	s_add_i32 s12, s12, s14
	v_mul_f32_e32 v0, 0x4f7ffffe, v0
	v_cvt_u32_f32_e32 v0, v0
	s_abs_i32 s18, s12
	s_ashr_i32 s14, s12, 31
	v_readlane_b32 s0, v241, 11
	v_readfirstlane_b32 s27, v0
	s_mul_i32 s26, s26, s27
	s_mul_hi_u32 s26, s27, s26
	s_add_i32 s27, s27, s26
	s_mul_hi_u32 s27, s18, s27
	s_mul_i32 s26, s27, s15
	s_sub_i32 s18, s18, s26
	s_add_i32 s28, s27, 1
	s_sub_i32 s29, s18, s15
	s_cmp_ge_u32 s18, s15
	s_cselect_b32 s27, s28, s27
	s_cselect_b32 s18, s29, s18
	s_add_i32 s28, s27, 1
	s_cmp_ge_u32 s18, s15
	s_cselect_b32 s18, s28, s27
	s_xor_b32 s18, s18, s14
	s_sub_i32 s14, s18, s14
	s_add_i32 s12, s12, s13
	s_mul_i32 s13, s14, s15
	s_sub_i32 s12, s12, s13
	s_ashr_i32 s13, s12, 31
	s_lshl_b64 s[28:29], s[12:13], 19
	v_readlane_b32 s1, v241, 12
	s_add_u32 s28, s0, s28
	s_addc_u32 s29, s1, s29
	s_ashr_i32 s15, s14, 31
	v_mov_b32_e32 v8, v178
	s_lshl_b64 s[30:31], s[14:15], 18
	v_readlane_b32 s0, v244, 42
	s_add_u32 s30, s0, s30
	v_ashrrev_i32_e32 v4, 3, v8
	v_readlane_b32 s0, v244, 43
	v_ashrrev_i32_e32 v5, 31, v4
	s_addc_u32 s31, s0, s31
	v_lshlrev_b64 v[6:7], 11, v[4:5]
	v_lshlrev_b32_e32 v2, 4, v8
	v_lshrrev_b32_e32 v5, 4, v8
	v_lshl_add_u64 v[0:1], s[28:29], 0, v[6:7]
	v_and_b32_e32 v2, 0x70, v2
	v_lshl_add_u64 v[6:7], s[30:31], 0, v[6:7]
	v_xor_b32_e32 v10, v5, v8
	v_lshl_add_u64 v[0:1], v[0:1], 0, v[2:3]
	v_bfe_u32 v9, v8, 1, 3
	v_lshl_add_u64 v[132:133], v[6:7], 0, v[2:3]
	v_lshlrev_b32_e32 v2, 4, v10
	v_lshlrev_b32_e32 v7, 7, v8
	v_and_b32_e32 v2, 0x70, v2
	v_bitop3_b32 v5, v5, v9, 3 bitop3:0x6c
	v_bfe_u32 v6, v8, 4, 2
	v_and_b32_e32 v8, 0xffffc780, v7
	v_lshl_or_b32 v2, v4, 7, v2
	v_and_b32_e32 v4, 0x2780, v7
	v_lshlrev_b32_e32 v5, 4, v5
	s_waitcnt vmcnt(8)
	v_or_b32_e32 v140, v4, v5
	v_or_b32_e32 v141, v8, v5
	v_bitop3_b32 v5, v6, v9, 4 bitop3:0x36
	v_lshlrev_b32_e32 v5, 4, v5
	s_waitcnt vmcnt(4)
	v_mov_b32_e32 v28, 0
	s_mov_b32 s26, 1
	v_or_b32_e32 v142, v4, v5
	v_or_b32_e32 v143, v8, v5
	v_mov_b64_e32 v[134:135], v[0:1]
	v_mov_b64_e32 v[136:137], v[132:133]
	v_mov_b32_e32 v29, v28
	v_mov_b32_e32 v30, v28
	v_mov_b32_e32 v31, v28
	v_mov_b32_e32 v4, v28
	v_mov_b32_e32 v5, v28
	v_mov_b32_e32 v6, v28
	v_mov_b32_e32 v7, v28
	v_mov_b32_e32 v8, v28
	v_mov_b32_e32 v9, v28
	v_mov_b32_e32 v10, v28
	v_mov_b32_e32 v11, v28
	v_mov_b32_e32 v12, v28
	v_mov_b32_e32 v13, v28
	v_mov_b32_e32 v14, v28
	v_mov_b32_e32 v15, v28
	v_mov_b32_e32 v16, v28
	v_mov_b32_e32 v17, v28
	v_mov_b32_e32 v18, v28
	v_mov_b32_e32 v19, v28
	v_mov_b32_e32 v20, v28
	v_mov_b32_e32 v21, v28
	v_mov_b32_e32 v22, v28
	v_mov_b32_e32 v23, v28
	v_mov_b32_e32 v24, v28
	v_mov_b32_e32 v25, v28
	v_mov_b32_e32 v26, v28
	v_mov_b32_e32 v27, v28
	v_mov_b32_e32 v32, v28
	v_mov_b32_e32 v33, v28
	v_mov_b32_e32 v34, v28
	v_mov_b32_e32 v35, v28
	v_mov_b32_e32 v36, v28
	v_mov_b32_e32 v37, v28
	v_mov_b32_e32 v38, v28
	v_mov_b32_e32 v39, v28
	v_mov_b32_e32 v40, v28
	v_mov_b32_e32 v41, v28
	v_mov_b32_e32 v42, v28
	v_mov_b32_e32 v43, v28
	v_mov_b32_e32 v44, v28
	v_mov_b32_e32 v45, v28
	v_mov_b32_e32 v46, v28
	v_mov_b32_e32 v47, v28
	v_mov_b32_e32 v48, v28
	v_mov_b32_e32 v49, v28
	v_mov_b32_e32 v50, v28
	v_mov_b32_e32 v51, v28
	v_mov_b32_e32 v52, v28
	v_mov_b32_e32 v53, v28
	v_mov_b32_e32 v54, v28
	v_mov_b32_e32 v55, v28
	v_mov_b32_e32 v56, v28
	v_mov_b32_e32 v57, v28
	v_mov_b32_e32 v58, v28
	v_mov_b32_e32 v59, v28
	v_mov_b32_e32 v60, v28
	v_mov_b32_e32 v61, v28
	v_mov_b32_e32 v62, v28
	v_mov_b32_e32 v63, v28
	v_mov_b32_e32 v64, v28
	v_mov_b32_e32 v65, v28
	v_mov_b32_e32 v66, v28
	v_mov_b32_e32 v67, v28
	v_mov_b32_e32 v68, v28
	v_mov_b32_e32 v69, v28
	v_mov_b32_e32 v70, v28
	v_mov_b32_e32 v71, v28
	v_mov_b32_e32 v72, v28
	v_mov_b32_e32 v73, v28
	v_mov_b32_e32 v74, v28
	v_mov_b32_e32 v75, v28
	v_mov_b32_e32 v76, v28
	v_mov_b32_e32 v77, v28
	v_mov_b32_e32 v78, v28
	v_mov_b32_e32 v79, v28
	v_mov_b32_e32 v80, v28
	v_mov_b32_e32 v81, v28
	v_mov_b32_e32 v82, v28
	v_mov_b32_e32 v83, v28
	v_mov_b32_e32 v84, v28
	v_mov_b32_e32 v85, v28
	v_mov_b32_e32 v86, v28
	v_mov_b32_e32 v87, v28
	v_mov_b32_e32 v88, v28
	v_mov_b32_e32 v89, v28
	v_mov_b32_e32 v90, v28
	v_mov_b32_e32 v91, v28
	v_mov_b32_e32 v92, v28
	v_mov_b32_e32 v93, v28
	v_mov_b32_e32 v94, v28
	v_mov_b32_e32 v95, v28
	v_mov_b32_e32 v96, v28
	v_mov_b32_e32 v97, v28
	v_mov_b32_e32 v98, v28
	v_mov_b32_e32 v99, v28
	v_mov_b32_e32 v100, v28
	v_mov_b32_e32 v101, v28
	v_mov_b32_e32 v102, v28
	v_mov_b32_e32 v103, v28
	v_mov_b32_e32 v104, v28
	v_mov_b32_e32 v105, v28
	v_mov_b32_e32 v106, v28
	v_mov_b32_e32 v107, v28
	v_mov_b32_e32 v108, v28
	v_mov_b32_e32 v109, v28
	v_mov_b32_e32 v110, v28
	v_mov_b32_e32 v111, v28
	v_mov_b32_e32 v112, v28
	v_mov_b32_e32 v113, v28
	v_mov_b32_e32 v114, v28
	v_mov_b32_e32 v115, v28
	v_mov_b32_e32 v116, v28
	v_mov_b32_e32 v117, v28
	v_mov_b32_e32 v118, v28
	v_mov_b32_e32 v119, v28
	v_mov_b32_e32 v120, v28
	v_mov_b32_e32 v121, v28
	v_mov_b32_e32 v122, v28
	v_mov_b32_e32 v123, v28
	v_mov_b32_e32 v124, v28
	v_mov_b32_e32 v125, v28
	v_mov_b32_e32 v126, v28
	v_mov_b32_e32 v127, v28
	v_mov_b32_e32 v128, v28
	v_mov_b32_e32 v129, v28
	v_mov_b32_e32 v130, v28
	v_mov_b32_e32 v131, v28
	s_mov_b32 s0, 0x30000
	s_mov_b32 s1, 0x10000
	s_nop 0
	v_lshrrev_b32_e32 v232, 3, v178
	v_and_b32_e32 v233, 7, v178
	v_bfe_u32 v234, v178, 4, 3
	v_xor_b32_e32 v233, v233, v234
	v_lshrrev_b32_e32 v234, 6, v178
	v_lshlrev_b32_e32 v232, 11, v232
	v_lshl_add_u32 v224, v233, 4, v232
	v_add_u32_e32 v225, 0x10000, v224
	v_add_u32_e32 v226, 0x20000, v224
	v_add_u32_e32 v227, 0x30000, v224
	v_add_u32_e32 v228, 0x40000, v224
	v_add_u32_e32 v229, 0x50000, v224
	v_add_u32_e32 v230, 0x60000, v224
	v_add_u32_e32 v231, 0x70000, v224
	v_readfirstlane_b32 s15, v234
	s_lshl_b32 s15, s15, 10
; __device__ __forceinline__ void gemm_core_big(const bf16_t* __restrict__ A, int lda, const bf16_t* __restrict__ Bt, int ldb,
;                                               int K, f32x4 (&acc)[8][4], char* smem) {
;     ...
;   for (int kt = 0; kt < nk; ++kt) {
;     __syncthreads();
; #pragma unroll
;     for (int i = 0; i < 8; ++i) *(u32x4*)(wA + 32 * i * LDS_STRIDE) = ra[i];
; #pragma unroll
;     for (int i = 0; i < 4; ++i) *(u32x4*)(wB + 32 * i * LDS_STRIDE) = rb[i];
;     __syncthreads();
;     {
;       const int k1 = min(kt + 1, nk - 1) << 6;
; #pragma unroll
;       for (int i = 0; i < 8; ++i) ra[i] = *(const u32x4*)(ap + (size_t)(32 * i) * lda + k1);
; #pragma unroll
;       for (int i = 0; i < 4; ++i) rb[i] = *(const u32x4*)(bp + (size_t)(32 * i) * ldb + k1);
;     }
; #pragma unroll
;     for (int ks = 0; ks < 2; ++ks) {
;       const int fo = ks ? fo1 : fo0;
;       bf16x8 bfr[4];
; #pragma unroll
;       for (int j = 0; j < 4; ++j) bfr[j] = *(const bf16x8*)(cB + j * 16 * LDS_STRIDE + fo);
; #pragma unroll
;       for (int i = 0; i < 8; ++i) {
;         const bf16x8 af = *(const bf16x8*)(cA + i * 16 * LDS_STRIDE + fo);
; #pragma unroll
;         for (int j = 0; j < 4; ++j)
;           acc[i][j] = __builtin_amdgcn_mfma_f32_16x16x32_bf16(bfr[j], af, acc[i][j], 0, 0, 0);
;       }
;     }
;   }
.LBB0_711:
	s_setprio 0
	s_barrier
	s_add_i32 m0, s15, 0x8000
	s_nop 0
	global_load_lds_dwordx4 v224, s[30:31]
	s_mov_b32 m0, s15
	s_nop 0
	global_load_lds_dwordx4 v224, s[28:29]
	s_add_i32 m0, s15, 0x1000
	s_nop 0
	global_load_lds_dwordx4 v225, s[28:29]
	s_add_i32 m0, s15, 0x2000
	s_nop 0
	global_load_lds_dwordx4 v226, s[28:29]
	s_add_i32 m0, s15, 0x3000
	s_nop 0
	global_load_lds_dwordx4 v227, s[28:29]
	s_add_i32 m0, s15, 0x4000
	s_nop 0
	global_load_lds_dwordx4 v228, s[28:29]
	s_add_i32 m0, s15, 0x5000
	s_nop 0
	global_load_lds_dwordx4 v229, s[28:29]
	s_add_i32 m0, s15, 0x6000
	s_nop 0
	global_load_lds_dwordx4 v230, s[28:29]
	s_add_i32 m0, s15, 0x7000
	s_nop 0
	global_load_lds_dwordx4 v231, s[28:29]
	s_add_i32 m0, s15, 0x9000
	s_nop 0
	global_load_lds_dwordx4 v225, s[30:31]
	s_add_i32 m0, s15, 0xa000
	s_nop 0
	global_load_lds_dwordx4 v226, s[30:31]
	s_add_i32 m0, s15, 0xb000
	s_nop 0
	global_load_lds_dwordx4 v227, s[30:31]
	s_add_u32 s28, s28, 0x80
	s_addc_u32 s29, s29, 0
	s_add_u32 s30, s30, 0x80
	s_addc_u32 s31, s31, 0
	s_add_i32 s26, s26, 1
	s_lshl_b32 s18, s13, 7
	s_cmp_lg_u32 s26, 17
	s_waitcnt vmcnt(0)
	s_barrier
	ds_read_b128 v[134:137], v140 offset:32768
	ds_read_b128 v[144:147], v140 offset:34816
	ds_read_b128 v[156:159], v140 offset:36864
	ds_read_b128 v[160:163], v140 offset:38912
	ds_read_b128 v[148:151], v141 offset:0
	ds_read_b128 v[152:155], v141 offset:2048
	ds_read_b128 v[216:219], v141 offset:4096
	ds_read_b128 v[220:223], v141 offset:6144
	s_setprio 1
	s_waitcnt lgkmcnt(3)
	v_mfma_f32_16x16x32_bf16 v[128:131], v[134:137], v[148:151], v[128:131]
	v_mfma_f32_16x16x32_bf16 v[124:127], v[144:147], v[148:151], v[124:127]
	v_mfma_f32_16x16x32_bf16 v[120:123], v[156:159], v[148:151], v[120:123]
	v_mfma_f32_16x16x32_bf16 v[116:119], v[160:163], v[148:151], v[116:119]
	s_waitcnt lgkmcnt(2)
	v_mfma_f32_16x16x32_bf16 v[112:115], v[134:137], v[152:155], v[112:115]
	v_mfma_f32_16x16x32_bf16 v[108:111], v[144:147], v[152:155], v[108:111]
	v_mfma_f32_16x16x32_bf16 v[104:107], v[156:159], v[152:155], v[104:107]
	v_mfma_f32_16x16x32_bf16 v[100:103], v[160:163], v[152:155], v[100:103]
	ds_read_b128 v[148:151], v141 offset:8192
	ds_read_b128 v[152:155], v141 offset:10240
	s_waitcnt lgkmcnt(3)
	v_mfma_f32_16x16x32_bf16 v[96:99], v[134:137], v[216:219], v[96:99]
	v_mfma_f32_16x16x32_bf16 v[92:95], v[144:147], v[216:219], v[92:95]
	v_mfma_f32_16x16x32_bf16 v[88:91], v[156:159], v[216:219], v[88:91]
	v_mfma_f32_16x16x32_bf16 v[84:87], v[160:163], v[216:219], v[84:87]
	s_waitcnt lgkmcnt(2)
	v_mfma_f32_16x16x32_bf16 v[80:83], v[134:137], v[220:223], v[80:83]
	v_mfma_f32_16x16x32_bf16 v[76:79], v[144:147], v[220:223], v[76:79]
	v_mfma_f32_16x16x32_bf16 v[72:75], v[156:159], v[220:223], v[72:75]
	v_mfma_f32_16x16x32_bf16 v[68:71], v[160:163], v[220:223], v[68:71]
	ds_read_b128 v[216:219], v141 offset:12288
	ds_read_b128 v[220:223], v141 offset:14336
	ds_read_b128 v[200:203], v142 offset:32768
	ds_read_b128 v[204:207], v142 offset:34816
	ds_read_b128 v[208:211], v142 offset:36864
	ds_read_b128 v[212:215], v142 offset:38912
	s_waitcnt lgkmcnt(7)
	v_mfma_f32_16x16x32_bf16 v[64:67], v[134:137], v[148:151], v[64:67]
	v_mfma_f32_16x16x32_bf16 v[60:63], v[144:147], v[148:151], v[60:63]
	v_mfma_f32_16x16x32_bf16 v[56:59], v[156:159], v[148:151], v[56:59]
	v_mfma_f32_16x16x32_bf16 v[52:55], v[160:163], v[148:151], v[52:55]
	s_waitcnt lgkmcnt(6)
	v_mfma_f32_16x16x32_bf16 v[48:51], v[134:137], v[152:155], v[48:51]
	v_mfma_f32_16x16x32_bf16 v[44:47], v[144:147], v[152:155], v[44:47]
	v_mfma_f32_16x16x32_bf16 v[40:43], v[156:159], v[152:155], v[40:43]
	v_mfma_f32_16x16x32_bf16 v[36:39], v[160:163], v[152:155], v[36:39]
	ds_read_b128 v[148:151], v143 offset:0
	ds_read_b128 v[152:155], v143 offset:2048
	s_waitcnt lgkmcnt(7)
	v_mfma_f32_16x16x32_bf16 v[32:35], v[134:137], v[216:219], v[32:35]
	v_mfma_f32_16x16x32_bf16 v[24:27], v[144:147], v[216:219], v[24:27]
	v_mfma_f32_16x16x32_bf16 v[20:23], v[156:159], v[216:219], v[20:23]
	v_mfma_f32_16x16x32_bf16 v[16:19], v[160:163], v[216:219], v[16:19]
	s_waitcnt lgkmcnt(6)
	v_mfma_f32_16x16x32_bf16 v[12:15], v[134:137], v[220:223], v[12:15]
	v_mfma_f32_16x16x32_bf16 v[8:11], v[144:147], v[220:223], v[8:11]
	v_mfma_f32_16x16x32_bf16 v[4:7], v[156:159], v[220:223], v[4:7]
	v_mfma_f32_16x16x32_bf16 v[28:31], v[160:163], v[220:223], v[28:31]
	ds_read_b128 v[216:219], v143 offset:4096
	ds_read_b128 v[220:223], v143 offset:6144
	s_waitcnt lgkmcnt(3)
	v_mfma_f32_16x16x32_bf16 v[128:131], v[200:203], v[148:151], v[128:131]
	v_mfma_f32_16x16x32_bf16 v[124:127], v[204:207], v[148:151], v[124:127]
	v_mfma_f32_16x16x32_bf16 v[120:123], v[208:211], v[148:151], v[120:123]
	v_mfma_f32_16x16x32_bf16 v[116:119], v[212:215], v[148:151], v[116:119]
	s_waitcnt lgkmcnt(2)
	v_mfma_f32_16x16x32_bf16 v[112:115], v[200:203], v[152:155], v[112:115]
	v_mfma_f32_16x16x32_bf16 v[108:111], v[204:207], v[152:155], v[108:111]
	v_mfma_f32_16x16x32_bf16 v[104:107], v[208:211], v[152:155], v[104:107]
	v_mfma_f32_16x16x32_bf16 v[100:103], v[212:215], v[152:155], v[100:103]
	ds_read_b128 v[148:151], v143 offset:8192
	ds_read_b128 v[152:155], v143 offset:10240
	s_waitcnt lgkmcnt(3)
	v_mfma_f32_16x16x32_bf16 v[96:99], v[200:203], v[216:219], v[96:99]
	v_mfma_f32_16x16x32_bf16 v[92:95], v[204:207], v[216:219], v[92:95]
	v_mfma_f32_16x16x32_bf16 v[88:91], v[208:211], v[216:219], v[88:91]
	v_mfma_f32_16x16x32_bf16 v[84:87], v[212:215], v[216:219], v[84:87]
	s_waitcnt lgkmcnt(2)
	v_mfma_f32_16x16x32_bf16 v[80:83], v[200:203], v[220:223], v[80:83]
	v_mfma_f32_16x16x32_bf16 v[76:79], v[204:207], v[220:223], v[76:79]
	v_mfma_f32_16x16x32_bf16 v[72:75], v[208:211], v[220:223], v[72:75]
	v_mfma_f32_16x16x32_bf16 v[68:71], v[212:215], v[220:223], v[68:71]
	ds_read_b128 v[216:219], v143 offset:12288
	ds_read_b128 v[220:223], v143 offset:14336
	s_waitcnt lgkmcnt(3)
	v_mfma_f32_16x16x32_bf16 v[64:67], v[200:203], v[148:151], v[64:67]
	v_mfma_f32_16x16x32_bf16 v[60:63], v[204:207], v[148:151], v[60:63]
	v_mfma_f32_16x16x32_bf16 v[56:59], v[208:211], v[148:151], v[56:59]
	v_mfma_f32_16x16x32_bf16 v[52:55], v[212:215], v[148:151], v[52:55]
	s_waitcnt lgkmcnt(2)
	v_mfma_f32_16x16x32_bf16 v[48:51], v[200:203], v[152:155], v[48:51]
	v_mfma_f32_16x16x32_bf16 v[44:47], v[204:207], v[152:155], v[44:47]
	v_mfma_f32_16x16x32_bf16 v[40:43], v[208:211], v[152:155], v[40:43]
	v_mfma_f32_16x16x32_bf16 v[36:39], v[212:215], v[152:155], v[36:39]
	s_waitcnt lgkmcnt(1)
	v_mfma_f32_16x16x32_bf16 v[32:35], v[200:203], v[216:219], v[32:35]
	v_mfma_f32_16x16x32_bf16 v[24:27], v[204:207], v[216:219], v[24:27]
	v_mfma_f32_16x16x32_bf16 v[20:23], v[208:211], v[216:219], v[20:23]
	v_mfma_f32_16x16x32_bf16 v[16:19], v[212:215], v[216:219], v[16:19]
	s_waitcnt lgkmcnt(0)
	v_mfma_f32_16x16x32_bf16 v[12:15], v[200:203], v[220:223], v[12:15]
	v_mfma_f32_16x16x32_bf16 v[8:11], v[204:207], v[220:223], v[8:11]
	v_mfma_f32_16x16x32_bf16 v[4:7], v[208:211], v[220:223], v[4:7]
	v_mfma_f32_16x16x32_bf16 v[28:31], v[212:215], v[220:223], v[28:31]
	s_cbranch_scc1 .LBB0_711
; __device__ __forceinline__ unsigned pack2(float a, float b) { return (unsigned)f2bf(a) | ((unsigned)f2bf(b) << 16); }
; __device__ __forceinline__ void phase_gemm_in(const Params& p, char* smem) {
;     ...
;     bf16_t* dst; int ldd, ncol0;
;     if (nt < PRE_W / 128) { dst = PRE; ldd = PRE_W; ncol0 = nt * 128; }
;     else { dst = POST; ldd = POST_W; ncol0 = (nt - PRE_W / 128) * 128; }
; #pragma unroll
;     for (int i = 0; i < 8; ++i) {
;       const int m = mt * 256 + wm * 128 + i * 16 + (lane & 15);
; #pragma unroll
;       for (int j = 0; j < 4; ++j) {
;         const int n = ncol0 + wn * 64 + j * 16 + (lane >> 4) * 4;
;         uint2 o;
;         o.x = pack2(acc[i][j][0], acc[i][j][1]);
;         o.y = pack2(acc[i][j][2], acc[i][j][3]);
;         *(uint2*)(dst + (size_t)m * ldd + n) = o;
;       }
;     }
	s_setprio 0
	s_lshl_b32 s13, s14, 7
	s_add_i32 s15, s13, 0xffffef00
	s_cmp_lt_i32 s14, 34
	s_mov_b32 s14, 0x4100000
	s_cselect_b32 s18, s14, 0xcb20000
	s_movk_i32 s0, 0x1200
	s_cselect_b32 s15, s13, s15
	s_cselect_b32 s14, 0x1100, s0
	v_lshl_add_u32 v2, s12, 8, v138
	s_add_u32 s12, s10, s18
	v_or_b32_e32 v0, s15, v139
	s_addc_u32 s13, s11, 0
	s_lshl_b32 s18, s14, 4
	v_ashrrev_i32_e32 v1, 31, v0
	v_lshlrev_b64 v[0:1], 1, v[0:1]
	v_bfe_u32 v136, v178, 4, 1
	v_mul_u32_u24_e32 v136, 24, v136
	v_add_u32_e32 v0, v0, v136
	v_bfe_u32 v136, v178, 3, 1
	v_lshlrev_b32_e32 v136, 6, v136
	v_add_u32_e32 v0, v0, v136
	v_and_b32_e32 v2, 0xfffffff7, v2
	v_mad_i64_i32 v[132:133], s[26:27], s14, v2, 0
	v_lshl_add_u64 v[132:133], v[132:133], 1, s[12:13]
	v_lshl_add_u64 v[132:133], v[132:133], 0, v[0:1]
	v_lshl_add_u64 v[134:135], v[132:133], 0, s[18:19]
	v_cvt_pk_bf16_f32 v144, v128, v129
	v_cvt_pk_bf16_f32 v146, v124, v125
	v_cvt_pk_bf16_f32 v145, v130, v131
	v_cvt_pk_bf16_f32 v147, v126, v127
	v_cvt_pk_bf16_f32 v148, v120, v121
	v_cvt_pk_bf16_f32 v150, v116, v117
	v_cvt_pk_bf16_f32 v149, v122, v123
	v_cvt_pk_bf16_f32 v151, v118, v119
	v_permlane16_swap_b32_e32 v144, v146
	v_permlane16_swap_b32_e32 v145, v147
	v_permlane16_swap_b32_e32 v148, v150
	v_permlane16_swap_b32_e32 v149, v151
	v_mov_b32_e32 v152, v144
	v_mov_b32_e32 v153, v145
	v_mov_b32_e32 v154, v146
	v_mov_b32_e32 v155, v147
	v_mov_b32_dpp v144, v148 row_ror:8 row_mask:0xf bank_mask:0xc
	v_mov_b32_dpp v145, v149 row_ror:8 row_mask:0xf bank_mask:0xc
	v_mov_b32_dpp v146, v150 row_ror:8 row_mask:0xf bank_mask:0xc
	v_mov_b32_dpp v147, v151 row_ror:8 row_mask:0xf bank_mask:0xc
	v_mov_b32_dpp v148, v152 row_ror:8 row_mask:0xf bank_mask:0x3
	v_mov_b32_dpp v149, v153 row_ror:8 row_mask:0xf bank_mask:0x3
	v_mov_b32_dpp v150, v154 row_ror:8 row_mask:0xf bank_mask:0x3
	v_mov_b32_dpp v151, v155 row_ror:8 row_mask:0xf bank_mask:0x3
	global_store_dwordx4 v[132:133], v[144:147], off nt
	global_store_dwordx4 v[134:135], v[148:151], off nt
	v_or_b32_e32 v172, 0x10, v2
	v_mad_i64_i32 v[168:169], s[26:27], s14, v172, 0
	v_lshl_add_u64 v[168:169], v[168:169], 1, s[12:13]
	v_lshl_add_u64 v[168:169], v[168:169], 0, v[0:1]
	v_lshl_add_u64 v[170:171], v[168:169], 0, s[18:19]
	v_cvt_pk_bf16_f32 v156, v112, v113
	v_cvt_pk_bf16_f32 v158, v108, v109
	v_cvt_pk_bf16_f32 v157, v114, v115
	v_cvt_pk_bf16_f32 v159, v110, v111
	v_cvt_pk_bf16_f32 v160, v104, v105
	v_cvt_pk_bf16_f32 v162, v100, v101
	v_cvt_pk_bf16_f32 v161, v106, v107
	v_cvt_pk_bf16_f32 v163, v102, v103
	v_permlane16_swap_b32_e32 v156, v158
	v_permlane16_swap_b32_e32 v157, v159
	v_permlane16_swap_b32_e32 v160, v162
	v_permlane16_swap_b32_e32 v161, v163
	v_mov_b32_e32 v164, v156
	v_mov_b32_e32 v165, v157
	v_mov_b32_e32 v166, v158
	v_mov_b32_e32 v167, v159
	v_mov_b32_dpp v156, v160 row_ror:8 row_mask:0xf bank_mask:0xc
	v_mov_b32_dpp v157, v161 row_ror:8 row_mask:0xf bank_mask:0xc
	v_mov_b32_dpp v158, v162 row_ror:8 row_mask:0xf bank_mask:0xc
	v_mov_b32_dpp v159, v163 row_ror:8 row_mask:0xf bank_mask:0xc
	v_mov_b32_dpp v160, v164 row_ror:8 row_mask:0xf bank_mask:0x3
	v_mov_b32_dpp v161, v165 row_ror:8 row_mask:0xf bank_mask:0x3
	v_mov_b32_dpp v162, v166 row_ror:8 row_mask:0xf bank_mask:0x3
	v_mov_b32_dpp v163, v167 row_ror:8 row_mask:0xf bank_mask:0x3
	global_store_dwordx4 v[168:169], v[156:159], off nt
	global_store_dwordx4 v[170:171], v[160:163], off nt
	v_or_b32_e32 v172, 0x20, v2
	v_mad_i64_i32 v[132:133], s[26:27], s14, v172, 0
	v_lshl_add_u64 v[132:133], v[132:133], 1, s[12:13]
	v_lshl_add_u64 v[132:133], v[132:133], 0, v[0:1]
	v_lshl_add_u64 v[134:135], v[132:133], 0, s[18:19]
	v_cvt_pk_bf16_f32 v144, v96, v97
	v_cvt_pk_bf16_f32 v146, v92, v93
	v_cvt_pk_bf16_f32 v145, v98, v99
	v_cvt_pk_bf16_f32 v147, v94, v95
	v_cvt_pk_bf16_f32 v148, v88, v89
	v_cvt_pk_bf16_f32 v150, v84, v85
	v_cvt_pk_bf16_f32 v149, v90, v91
	v_cvt_pk_bf16_f32 v151, v86, v87
	v_permlane16_swap_b32_e32 v144, v146
	v_permlane16_swap_b32_e32 v145, v147
	v_permlane16_swap_b32_e32 v148, v150
	v_permlane16_swap_b32_e32 v149, v151
	v_mov_b32_e32 v152, v144
	v_mov_b32_e32 v153, v145
	v_mov_b32_e32 v154, v146
	v_mov_b32_e32 v155, v147
	v_mov_b32_dpp v144, v148 row_ror:8 row_mask:0xf bank_mask:0xc
	v_mov_b32_dpp v145, v149 row_ror:8 row_mask:0xf bank_mask:0xc
	v_mov_b32_dpp v146, v150 row_ror:8 row_mask:0xf bank_mask:0xc
	v_mov_b32_dpp v147, v151 row_ror:8 row_mask:0xf bank_mask:0xc
	v_mov_b32_dpp v148, v152 row_ror:8 row_mask:0xf bank_mask:0x3
	v_mov_b32_dpp v149, v153 row_ror:8 row_mask:0xf bank_mask:0x3
	v_mov_b32_dpp v150, v154 row_ror:8 row_mask:0xf bank_mask:0x3
	v_mov_b32_dpp v151, v155 row_ror:8 row_mask:0xf bank_mask:0x3
	global_store_dwordx4 v[132:133], v[144:147], off nt
	global_store_dwordx4 v[134:135], v[148:151], off nt
	v_or_b32_e32 v172, 0x30, v2
	v_mad_i64_i32 v[168:169], s[26:27], s14, v172, 0
	v_lshl_add_u64 v[168:169], v[168:169], 1, s[12:13]
	v_lshl_add_u64 v[168:169], v[168:169], 0, v[0:1]
	v_lshl_add_u64 v[170:171], v[168:169], 0, s[18:19]
	v_cvt_pk_bf16_f32 v156, v80, v81
	v_cvt_pk_bf16_f32 v158, v76, v77
	v_cvt_pk_bf16_f32 v157, v82, v83
	v_cvt_pk_bf16_f32 v159, v78, v79
	v_cvt_pk_bf16_f32 v160, v72, v73
	v_cvt_pk_bf16_f32 v162, v68, v69
	v_cvt_pk_bf16_f32 v161, v74, v75
	v_cvt_pk_bf16_f32 v163, v70, v71
	v_permlane16_swap_b32_e32 v156, v158
	v_permlane16_swap_b32_e32 v157, v159
	v_permlane16_swap_b32_e32 v160, v162
	v_permlane16_swap_b32_e32 v161, v163
	v_mov_b32_e32 v164, v156
	v_mov_b32_e32 v165, v157
	v_mov_b32_e32 v166, v158
	v_mov_b32_e32 v167, v159
	v_mov_b32_dpp v156, v160 row_ror:8 row_mask:0xf bank_mask:0xc
	v_mov_b32_dpp v157, v161 row_ror:8 row_mask:0xf bank_mask:0xc
; __device__ __forceinline__ unsigned pack2(float a, float b) { return (unsigned)f2bf(a) | ((unsigned)f2bf(b) << 16); }
; __device__ __forceinline__ void phase_gemm_in(const Params& p, char* smem) {
;     ...
;   for (int it = 0; it < iters; ++it) {
;     int mt, nt;
;     if (!tile_at(it, MT, NTn, mt, nt)) break;
;     f32x4 acc[8][4];
; #pragma unroll
;     for (int i = 0; i < 8; ++i)
; #pragma unroll
;       for (int j = 0; j < 4; ++j) acc[i][j] = (f32x4){0.f, 0.f, 0.f, 0.f};
;     gemm_core_big(H + (size_t)mt * 256 * 1024, 1024, W + (size_t)nt * 128 * 1024, 1024, 1024, acc, smem);
;     bf16_t* dst; int ldd, ncol0;
;     if (nt < PRE_W / 128) { dst = PRE; ldd = PRE_W; ncol0 = nt * 128; }
;     else { dst = POST; ldd = POST_W; ncol0 = (nt - PRE_W / 128) * 128; }
; #pragma unroll
;     for (int i = 0; i < 8; ++i) {
;       const int m = mt * 256 + wm * 128 + i * 16 + (lane & 15);
; #pragma unroll
;       for (int j = 0; j < 4; ++j) {
;         const int n = ncol0 + wn * 64 + j * 16 + (lane >> 4) * 4;
;         uint2 o;
;         o.x = pack2(acc[i][j][0], acc[i][j][1]);
;         o.y = pack2(acc[i][j][2], acc[i][j][3]);
;         *(uint2*)(dst + (size_t)m * ldd + n) = o;
;       }
;     }
	v_mov_b32_dpp v158, v162 row_ror:8 row_mask:0xf bank_mask:0xc
	v_mov_b32_dpp v159, v163 row_ror:8 row_mask:0xf bank_mask:0xc
	v_mov_b32_dpp v160, v164 row_ror:8 row_mask:0xf bank_mask:0x3
	v_mov_b32_dpp v161, v165 row_ror:8 row_mask:0xf bank_mask:0x3
	v_mov_b32_dpp v162, v166 row_ror:8 row_mask:0xf bank_mask:0x3
	v_mov_b32_dpp v163, v167 row_ror:8 row_mask:0xf bank_mask:0x3
	global_store_dwordx4 v[168:169], v[156:159], off nt
	global_store_dwordx4 v[170:171], v[160:163], off nt
	v_or_b32_e32 v172, 0x40, v2
	v_mad_i64_i32 v[132:133], s[26:27], s14, v172, 0
	v_lshl_add_u64 v[132:133], v[132:133], 1, s[12:13]
	v_lshl_add_u64 v[132:133], v[132:133], 0, v[0:1]
	v_lshl_add_u64 v[134:135], v[132:133], 0, s[18:19]
	v_cvt_pk_bf16_f32 v144, v64, v65
	v_cvt_pk_bf16_f32 v146, v60, v61
	v_cvt_pk_bf16_f32 v145, v66, v67
	v_cvt_pk_bf16_f32 v147, v62, v63
	v_cvt_pk_bf16_f32 v148, v56, v57
	v_cvt_pk_bf16_f32 v150, v52, v53
	v_cvt_pk_bf16_f32 v149, v58, v59
	v_cvt_pk_bf16_f32 v151, v54, v55
	v_permlane16_swap_b32_e32 v144, v146
	v_permlane16_swap_b32_e32 v145, v147
	v_permlane16_swap_b32_e32 v148, v150
	v_permlane16_swap_b32_e32 v149, v151
	v_mov_b32_e32 v152, v144
	v_mov_b32_e32 v153, v145
	v_mov_b32_e32 v154, v146
	v_mov_b32_e32 v155, v147
	v_mov_b32_dpp v144, v148 row_ror:8 row_mask:0xf bank_mask:0xc
	v_mov_b32_dpp v145, v149 row_ror:8 row_mask:0xf bank_mask:0xc
	v_mov_b32_dpp v146, v150 row_ror:8 row_mask:0xf bank_mask:0xc
	v_mov_b32_dpp v147, v151 row_ror:8 row_mask:0xf bank_mask:0xc
	v_mov_b32_dpp v148, v152 row_ror:8 row_mask:0xf bank_mask:0x3
	v_mov_b32_dpp v149, v153 row_ror:8 row_mask:0xf bank_mask:0x3
	v_mov_b32_dpp v150, v154 row_ror:8 row_mask:0xf bank_mask:0x3
	v_mov_b32_dpp v151, v155 row_ror:8 row_mask:0xf bank_mask:0x3
	global_store_dwordx4 v[132:133], v[144:147], off nt
	global_store_dwordx4 v[134:135], v[148:151], off nt
	v_or_b32_e32 v172, 0x50, v2
	v_mad_i64_i32 v[168:169], s[26:27], s14, v172, 0
	v_lshl_add_u64 v[168:169], v[168:169], 1, s[12:13]
	v_lshl_add_u64 v[168:169], v[168:169], 0, v[0:1]
	v_lshl_add_u64 v[170:171], v[168:169], 0, s[18:19]
	v_cvt_pk_bf16_f32 v156, v48, v49
	v_cvt_pk_bf16_f32 v158, v44, v45
	v_cvt_pk_bf16_f32 v157, v50, v51
	v_cvt_pk_bf16_f32 v159, v46, v47
	v_cvt_pk_bf16_f32 v160, v40, v41
	v_cvt_pk_bf16_f32 v162, v36, v37
	v_cvt_pk_bf16_f32 v161, v42, v43
	v_cvt_pk_bf16_f32 v163, v38, v39
	v_permlane16_swap_b32_e32 v156, v158
	v_permlane16_swap_b32_e32 v157, v159
	v_permlane16_swap_b32_e32 v160, v162
	v_permlane16_swap_b32_e32 v161, v163
	v_mov_b32_e32 v164, v156
	v_mov_b32_e32 v165, v157
	v_mov_b32_e32 v166, v158
	v_mov_b32_e32 v167, v159
	v_mov_b32_dpp v156, v160 row_ror:8 row_mask:0xf bank_mask:0xc
	v_mov_b32_dpp v157, v161 row_ror:8 row_mask:0xf bank_mask:0xc
	v_mov_b32_dpp v158, v162 row_ror:8 row_mask:0xf bank_mask:0xc
	v_mov_b32_dpp v159, v163 row_ror:8 row_mask:0xf bank_mask:0xc
	v_mov_b32_dpp v160, v164 row_ror:8 row_mask:0xf bank_mask:0x3
	v_mov_b32_dpp v161, v165 row_ror:8 row_mask:0xf bank_mask:0x3
	v_mov_b32_dpp v162, v166 row_ror:8 row_mask:0xf bank_mask:0x3
	v_mov_b32_dpp v163, v167 row_ror:8 row_mask:0xf bank_mask:0x3
	global_store_dwordx4 v[168:169], v[156:159], off nt
	global_store_dwordx4 v[170:171], v[160:163], off nt
	v_or_b32_e32 v172, 0x60, v2
	v_mad_i64_i32 v[132:133], s[26:27], s14, v172, 0
	v_lshl_add_u64 v[132:133], v[132:133], 1, s[12:13]
	v_lshl_add_u64 v[132:133], v[132:133], 0, v[0:1]
	v_lshl_add_u64 v[134:135], v[132:133], 0, s[18:19]
	v_cvt_pk_bf16_f32 v144, v32, v33
	v_cvt_pk_bf16_f32 v146, v24, v25
	v_cvt_pk_bf16_f32 v145, v34, v35
	v_cvt_pk_bf16_f32 v147, v26, v27
	v_cvt_pk_bf16_f32 v148, v20, v21
	v_cvt_pk_bf16_f32 v150, v16, v17
	v_cvt_pk_bf16_f32 v149, v22, v23
	v_cvt_pk_bf16_f32 v151, v18, v19
	v_permlane16_swap_b32_e32 v144, v146
	v_permlane16_swap_b32_e32 v145, v147
	v_permlane16_swap_b32_e32 v148, v150
	v_permlane16_swap_b32_e32 v149, v151
	v_mov_b32_e32 v152, v144
	v_mov_b32_e32 v153, v145
	v_mov_b32_e32 v154, v146
	v_mov_b32_e32 v155, v147
	v_mov_b32_dpp v144, v148 row_ror:8 row_mask:0xf bank_mask:0xc
	v_mov_b32_dpp v145, v149 row_ror:8 row_mask:0xf bank_mask:0xc
	v_mov_b32_dpp v146, v150 row_ror:8 row_mask:0xf bank_mask:0xc
	v_mov_b32_dpp v147, v151 row_ror:8 row_mask:0xf bank_mask:0xc
	v_mov_b32_dpp v148, v152 row_ror:8 row_mask:0xf bank_mask:0x3
	v_mov_b32_dpp v149, v153 row_ror:8 row_mask:0xf bank_mask:0x3
	v_mov_b32_dpp v150, v154 row_ror:8 row_mask:0xf bank_mask:0x3
	v_mov_b32_dpp v151, v155 row_ror:8 row_mask:0xf bank_mask:0x3
	global_store_dwordx4 v[132:133], v[144:147], off nt
	global_store_dwordx4 v[134:135], v[148:151], off nt
	v_or_b32_e32 v172, 0x70, v2
	v_mad_i64_i32 v[168:169], s[26:27], s14, v172, 0
	v_lshl_add_u64 v[168:169], v[168:169], 1, s[12:13]
	v_lshl_add_u64 v[168:169], v[168:169], 0, v[0:1]
	v_lshl_add_u64 v[170:171], v[168:169], 0, s[18:19]
	v_cvt_pk_bf16_f32 v156, v12, v13
	v_cvt_pk_bf16_f32 v158, v8, v9
	v_cvt_pk_bf16_f32 v157, v14, v15
	v_cvt_pk_bf16_f32 v159, v10, v11
	v_cvt_pk_bf16_f32 v160, v4, v5
	v_cvt_pk_bf16_f32 v162, v28, v29
	v_cvt_pk_bf16_f32 v161, v6, v7
	v_cvt_pk_bf16_f32 v163, v30, v31
	v_permlane16_swap_b32_e32 v156, v158
	v_permlane16_swap_b32_e32 v157, v159
	v_permlane16_swap_b32_e32 v160, v162
	v_permlane16_swap_b32_e32 v161, v163
	v_mov_b32_e32 v164, v156
	v_mov_b32_e32 v165, v157
	v_mov_b32_e32 v166, v158
	v_mov_b32_e32 v167, v159
	v_mov_b32_dpp v156, v160 row_ror:8 row_mask:0xf bank_mask:0xc
	v_mov_b32_dpp v157, v161 row_ror:8 row_mask:0xf bank_mask:0xc
	v_mov_b32_dpp v158, v162 row_ror:8 row_mask:0xf bank_mask:0xc
	v_mov_b32_dpp v159, v163 row_ror:8 row_mask:0xf bank_mask:0xc
	v_mov_b32_dpp v160, v164 row_ror:8 row_mask:0xf bank_mask:0x3
	v_mov_b32_dpp v161, v165 row_ror:8 row_mask:0xf bank_mask:0x3
	v_mov_b32_dpp v162, v166 row_ror:8 row_mask:0xf bank_mask:0x3
	v_mov_b32_dpp v163, v167 row_ror:8 row_mask:0xf bank_mask:0x3
	global_store_dwordx4 v[168:169], v[156:159], off nt
	global_store_dwordx4 v[170:171], v[160:163], off nt
	s_add_i32 s23, s23, 1
	s_cmp_eq_u32 s23, s17
	s_cselect_b64 s[12:13], -1, 0
	s_mov_b32 s31, 0x18000
	s_branch .LBB0_708
